# rg_in and gates: first-iteration waits after the epilogue tightened to vmcnt(12)
# baseline (speedup 1.0000x reference)
.LBB0_110:
	ds_read_b128 v[156:159], v150
	ds_read_b128 v[160:163], v150 offset:1024
	ds_read_b128 v[164:167], v150 offset:2048
	ds_read_b128 v[168:171], v150 offset:3072
	ds_read_b128 v[172:175], v151
	ds_read_b128 v[184:187], v151 offset:1024
	ds_read_b128 v[188:191], v151 offset:2048
	ds_read_b128 v[192:195], v151 offset:3072
	s_add_u32 s8, s94, 0xfffc0080
	s_addc_u32 s9, s95, -1
	s_cmp_eq_u32 s42, 12
	s_cselect_b32 s39, s7, s9
	s_cselect_b32 s38, s16, s8
	s_cselect_b32 s37, s17, s29
	s_cselect_b32 s36, s18, s28
	v_lshl_add_u64 v[146:147], s[94:95], 0, v[138:139]
	s_add_i32 m0, s15, 0xc000
	ds_read_b128 v[196:199], v154
	ds_read_b128 v[200:203], v154 offset:1024
	ds_read_b128 v[204:207], v154 offset:2048
	ds_read_b128 v[208:211], v154 offset:3072
	ds_read_b128 v[212:215], v154 offset:4096
	ds_read_b128 v[216:219], v154 offset:5120
	ds_read_b128 v[220:223], v154 offset:6144
	ds_read_b128 v[224:227], v154 offset:7168
	global_load_lds_dwordx4 v[146:147], off
	v_lshl_add_u64 v[146:147], s[94:95], 0, v[140:141]
	s_add_i32 m0, s15, 0xe000
	s_nop 0
	global_load_lds_dwordx4 v[146:147], off
	s_cmp_eq_u32 s99, 0
	s_cbranch_scc1 .Ldpw_0_0a
	s_waitcnt vmcnt(12)
	s_branch .Ldpw_0_0b

.Ldpw_0_0b:
	s_waitcnt lgkmcnt(0)
	s_barrier
	s_setprio 1
	s_waitcnt lgkmcnt(0)
	v_mfma_f32_16x16x32_bf16 v[124:127], v[156:159], v[196:199], v[124:127]
	v_mfma_f32_16x16x32_bf16 v[120:123], v[164:167], v[196:199], v[120:123]
	v_mfma_f32_16x16x32_bf16 v[108:111], v[156:159], v[204:207], v[108:111]
	v_mfma_f32_16x16x32_bf16 v[104:107], v[164:167], v[204:207], v[104:107]
	v_mfma_f32_16x16x32_bf16 v[92:95], v[156:159], v[212:215], v[92:95]
	v_mfma_f32_16x16x32_bf16 v[88:91], v[164:167], v[212:215], v[88:91]
	v_mfma_f32_16x16x32_bf16 v[76:79], v[156:159], v[220:223], v[76:79]
	v_mfma_f32_16x16x32_bf16 v[72:75], v[164:167], v[220:223], v[72:75]
	v_mfma_f32_16x16x32_bf16 v[124:127], v[160:163], v[200:203], v[124:127]
	v_mfma_f32_16x16x32_bf16 v[120:123], v[168:171], v[200:203], v[120:123]
	v_mfma_f32_16x16x32_bf16 v[108:111], v[160:163], v[208:211], v[108:111]
	v_mfma_f32_16x16x32_bf16 v[104:107], v[168:171], v[208:211], v[104:107]
	v_mfma_f32_16x16x32_bf16 v[92:95], v[160:163], v[216:219], v[92:95]
	v_mfma_f32_16x16x32_bf16 v[88:91], v[168:171], v[216:219], v[88:91]
	v_mfma_f32_16x16x32_bf16 v[76:79], v[160:163], v[224:227], v[76:79]
	v_mfma_f32_16x16x32_bf16 v[72:75], v[168:171], v[224:227], v[72:75]
	s_setprio 0
	s_setprio 1
	v_mfma_f32_16x16x32_bf16 v[116:119], v[172:175], v[196:199], v[116:119]
	v_mfma_f32_16x16x32_bf16 v[112:115], v[188:191], v[196:199], v[112:115]
	v_mfma_f32_16x16x32_bf16 v[100:103], v[172:175], v[204:207], v[100:103]
	v_mfma_f32_16x16x32_bf16 v[96:99], v[188:191], v[204:207], v[96:99]
	v_mfma_f32_16x16x32_bf16 v[84:87], v[172:175], v[212:215], v[84:87]
	v_mfma_f32_16x16x32_bf16 v[80:83], v[188:191], v[212:215], v[80:83]
	v_mfma_f32_16x16x32_bf16 v[68:71], v[172:175], v[220:223], v[68:71]
	v_mfma_f32_16x16x32_bf16 v[64:67], v[188:191], v[220:223], v[64:67]
	v_mfma_f32_16x16x32_bf16 v[116:119], v[184:187], v[200:203], v[116:119]
	v_mfma_f32_16x16x32_bf16 v[112:115], v[192:195], v[200:203], v[112:115]
	v_mfma_f32_16x16x32_bf16 v[100:103], v[184:187], v[208:211], v[100:103]
	v_mfma_f32_16x16x32_bf16 v[96:99], v[192:195], v[208:211], v[96:99]
	v_mfma_f32_16x16x32_bf16 v[84:87], v[184:187], v[216:219], v[84:87]
	v_mfma_f32_16x16x32_bf16 v[80:83], v[192:195], v[216:219], v[80:83]
	v_mfma_f32_16x16x32_bf16 v[68:71], v[184:187], v[224:227], v[68:71]
	v_mfma_f32_16x16x32_bf16 v[64:67], v[192:195], v[224:227], v[64:67]
	s_setprio 0
	s_barrier
	s_add_i32 s8, s74, s45
	v_lshl_add_u64 v[146:147], s[36:37], 0, v[130:131]
	s_mov_b32 m0, s8
	ds_read_b128 v[196:199], v154 offset:16384
	ds_read_b128 v[200:203], v154 offset:17408
	ds_read_b128 v[204:207], v154 offset:18432
	ds_read_b128 v[208:211], v154 offset:19456
	ds_read_b128 v[212:215], v154 offset:20480
	ds_read_b128 v[216:219], v154 offset:21504
	ds_read_b128 v[220:223], v154 offset:22528
	ds_read_b128 v[224:227], v154 offset:23552
	global_load_lds_dwordx4 v[146:147], off
	s_add_i32 m0, s8, 0x2000
	s_add_u32 s8, s36, 0x40000
	v_lshl_add_u64 v[228:229], s[36:37], 0, v[134:135]
	s_addc_u32 s9, s37, 0
	s_add_i32 s43, s75, s45
	global_load_lds_dwordx4 v[228:229], off
	v_lshl_add_u64 v[230:231], s[8:9], 0, v[130:131]
	s_mov_b32 m0, s43
	v_lshl_add_u64 v[232:233], s[38:39], 0, v[132:133]
	global_load_lds_dwordx4 v[230:231], off
	v_lshl_add_u64 v[230:231], s[8:9], 0, v[134:135]
	s_add_i32 m0, s43, 0x2000
	s_nop 0
	global_load_lds_dwordx4 v[230:231], off
	v_lshl_add_u64 v[230:231], s[38:39], 0, v[128:129]
	s_mov_b32 m0, s15
	s_nop 0
	global_load_lds_dwordx4 v[230:231], off
	s_mov_b32 m0, s48
	s_nop 0
	global_load_lds_dwordx4 v[232:233], off
	s_cmp_eq_u32 s99, 0
	s_cbranch_scc1 .Ldpw_0_1a
	s_waitcnt vmcnt(12)
	s_branch .Ldpw_0_1b

.LBB0_458:
	s_add_u32 s19, s82, s18
	s_addc_u32 s29, s83, 0
	s_add_u32 s38, s19, 0x100
	s_addc_u32 s39, s29, 0
	s_and_b64 s[8:9], s[36:37], exec
	s_cselect_b32 s49, s1, s39
	s_cselect_b32 s48, s16, s38
	s_add_u32 s8, s80, s18
	s_addc_u32 s9, s81, 0
	s_add_u32 s18, s8, 0x100
	s_addc_u32 s38, s9, 0
	s_and_b64 s[8:9], s[36:37], exec
	s_cselect_b32 s51, s17, s38
	s_cselect_b32 s50, s28, s18
	s_add_u32 s70, s19, 0x40080
	s_addc_u32 s71, s29, 0
	s_add_i32 vcc_hi, s91, s33
	ds_read_b128 v[28:31], v173
	ds_read_b128 v[32:35], v173 offset:1024
	ds_read_b128 v[40:43], v173 offset:2048
	ds_read_b128 v[44:47], v173 offset:3072
	ds_read_b128 v[144:147], v174
	ds_read_b128 v[148:151], v174 offset:1024
	ds_read_b128 v[166:169], v174 offset:2048
	ds_read_b128 v[188:191], v174 offset:3072
	s_add_i32 m0, s41, 0xc000
	s_add_i32 s76, s41, 0xe000
	s_add_i32 s97, vcc_hi, 0x2000
	s_add_u32 s68, s50, 0x10000
	s_addc_u32 s69, s51, 0
	s_add_i32 s9, s92, s33
	s_add_i32 s8, s9, 0x2000
	s_add_i32 vcc_lo, 0, 0x18000
	s_add_i32 s57, 0, 0x1c000
	s_add_u32 s38, s48, 0x40000
	s_addc_u32 s39, s49, 0
	s_add_i32 s47, vcc_lo, s33
	s_add_i32 s19, s47, 0x2000
	s_add_u32 s36, s50, 0x10080
	s_addc_u32 s37, s51, 0
	s_add_i32 s29, s57, s33
	s_add_i32 s18, s29, 0x2000
	v_lshl_add_u64 v[224:225], s[70:71], 0, v[160:161]
	ds_read_b128 v[192:195], v175
	ds_read_b128 v[196:199], v175 offset:1024
	ds_read_b128 v[200:203], v175 offset:2048
	ds_read_b128 v[204:207], v175 offset:3072
	ds_read_b128 v[208:211], v175 offset:4096
	ds_read_b128 v[212:215], v175 offset:5120
	ds_read_b128 v[216:219], v175 offset:6144
	ds_read_b128 v[220:223], v175 offset:7168
	global_load_lds_dwordx4 v[224:225], off
	v_lshl_add_u64 v[224:225], s[70:71], 0, v[156:157]
	s_mov_b32 m0, s76
	s_nop 0
	global_load_lds_dwordx4 v[224:225], off
	s_cmp_eq_u32 s99, 0
	s_cbranch_scc1 .Ldpw_1_0a
	s_waitcnt vmcnt(12)
	s_branch .Ldpw_1_0b

.Ldpw_1_0b:
	s_waitcnt lgkmcnt(0)
	s_barrier
	s_setprio 1
	s_waitcnt lgkmcnt(0)
	v_mfma_f32_16x16x32_bf16 v[140:143], v[28:31], v[192:195], v[140:143]
	v_mfma_f32_16x16x32_bf16 v[132:135], v[40:43], v[192:195], v[132:135]
	v_mfma_f32_16x16x32_bf16 v[124:127], v[28:31], v[200:203], v[124:127]
	v_mfma_f32_16x16x32_bf16 v[116:119], v[40:43], v[200:203], v[116:119]
	v_mfma_f32_16x16x32_bf16 v[108:111], v[28:31], v[208:211], v[108:111]
	v_mfma_f32_16x16x32_bf16 v[100:103], v[40:43], v[208:211], v[100:103]
	v_mfma_f32_16x16x32_bf16 v[92:95], v[28:31], v[216:219], v[92:95]
	v_mfma_f32_16x16x32_bf16 v[84:87], v[40:43], v[216:219], v[84:87]
	v_mfma_f32_16x16x32_bf16 v[140:143], v[32:35], v[196:199], v[140:143]
	v_mfma_f32_16x16x32_bf16 v[132:135], v[44:47], v[196:199], v[132:135]
	v_mfma_f32_16x16x32_bf16 v[124:127], v[32:35], v[204:207], v[124:127]
	v_mfma_f32_16x16x32_bf16 v[116:119], v[44:47], v[204:207], v[116:119]
	v_mfma_f32_16x16x32_bf16 v[108:111], v[32:35], v[212:215], v[108:111]
	v_mfma_f32_16x16x32_bf16 v[100:103], v[44:47], v[212:215], v[100:103]
	v_mfma_f32_16x16x32_bf16 v[92:95], v[32:35], v[220:223], v[92:95]
	v_mfma_f32_16x16x32_bf16 v[84:87], v[44:47], v[220:223], v[84:87]
	s_setprio 0
	s_setprio 1
	v_mfma_f32_16x16x32_bf16 v[136:139], v[144:147], v[192:195], v[136:139]
	v_mfma_f32_16x16x32_bf16 v[128:131], v[166:169], v[192:195], v[128:131]
	v_mfma_f32_16x16x32_bf16 v[120:123], v[144:147], v[200:203], v[120:123]
	v_mfma_f32_16x16x32_bf16 v[112:115], v[166:169], v[200:203], v[112:115]
	v_mfma_f32_16x16x32_bf16 v[104:107], v[144:147], v[208:211], v[104:107]
	v_mfma_f32_16x16x32_bf16 v[96:99], v[166:169], v[208:211], v[96:99]
	v_mfma_f32_16x16x32_bf16 v[88:91], v[144:147], v[216:219], v[88:91]
	v_mfma_f32_16x16x32_bf16 v[80:83], v[166:169], v[216:219], v[80:83]
	v_mfma_f32_16x16x32_bf16 v[136:139], v[148:151], v[196:199], v[136:139]
	v_mfma_f32_16x16x32_bf16 v[128:131], v[188:191], v[196:199], v[128:131]
	v_mfma_f32_16x16x32_bf16 v[120:123], v[148:151], v[204:207], v[120:123]
	v_mfma_f32_16x16x32_bf16 v[112:115], v[188:191], v[204:207], v[112:115]
	v_mfma_f32_16x16x32_bf16 v[104:107], v[148:151], v[212:215], v[104:107]
	v_mfma_f32_16x16x32_bf16 v[96:99], v[188:191], v[212:215], v[96:99]
	v_mfma_f32_16x16x32_bf16 v[88:91], v[148:151], v[220:223], v[88:91]
	v_mfma_f32_16x16x32_bf16 v[80:83], v[188:191], v[220:223], v[80:83]
	s_setprio 0
	s_barrier
	s_mov_b32 m0, vcc_hi
	v_lshl_add_u64 v[224:225], s[50:51], 0, v[158:159]
	ds_read_b128 v[192:195], v175 offset:16384
	ds_read_b128 v[196:199], v175 offset:17408
	ds_read_b128 v[200:203], v175 offset:18432
	ds_read_b128 v[204:207], v175 offset:19456
	ds_read_b128 v[208:211], v175 offset:20480
	ds_read_b128 v[212:215], v175 offset:21504
	ds_read_b128 v[216:219], v175 offset:22528
	ds_read_b128 v[220:223], v175 offset:23552
	global_load_lds_dwordx4 v[224:225], off
	v_lshl_add_u64 v[226:227], s[50:51], 0, v[154:155]
	s_mov_b32 m0, s97
	v_lshl_add_u64 v[228:229], s[68:69], 0, v[158:159]
	global_load_lds_dwordx4 v[226:227], off
	s_mov_b32 m0, s9
	v_lshl_add_u64 v[230:231], s[48:49], 0, v[156:157]
	global_load_lds_dwordx4 v[228:229], off
	v_lshl_add_u64 v[228:229], s[68:69], 0, v[154:155]
	s_mov_b32 m0, s8
	s_nop 0
	global_load_lds_dwordx4 v[228:229], off
	v_lshl_add_u64 v[228:229], s[48:49], 0, v[160:161]
	s_mov_b32 m0, s41
	s_nop 0
	global_load_lds_dwordx4 v[228:229], off
	s_mov_b32 m0, s77
	s_nop 0
	global_load_lds_dwordx4 v[230:231], off
	s_cmp_eq_u32 s99, 0
	s_cbranch_scc1 .Ldpw_1_1a
	s_waitcnt vmcnt(12)
	s_branch .Ldpw_1_1b
